# k17
# speedup vs baseline: 1.0091x; 1.0036x over previous
; __device__ __forceinline__ unsigned cvtpk(float lo, float hi) { f32x2 v = {lo, hi}; bf16x2_t b = __builtin_convertvector(v, bf16x2_t); return __builtin_bit_cast(unsigned, b); }
; __device__ __forceinline__ int lane_id_asm() { int l; asm volatile("v_mbcnt_lo_u32_b32 %0, -1, 0\n\tv_mbcnt_hi_u32_b32 %0, -1, %0" : "=v"(l)); return l; }
; __global__ void __launch_bounds__(NTHREADS, 2) mega_fwd(Params p) {
;     ...
;                     const int l3 = lane_id_asm(); bf16_t* orow = Ob + (size_t)(b * T + qb * 256 + wave * 32 + (l3 & 31)) * 1024 + hq * 64 + (l3 >> 5) * 4;
; #pragma unroll
;                     for (int i = 0; i < 2; ++i) { const float inv = __builtin_amdgcn_rcpf(lt[i]);
; #pragma unroll
;                         for (int db = 0; db < 2; ++db)
; #pragma unroll
;                             for (int g4 = 0; g4 < 4; ++g4) { u32x2 w; w.x = cvtpk(o[i][db][4 * g4] * inv, o[i][db][4 * g4 + 1] * inv); w.y = cvtpk(o[i][db][4 * g4 + 2] * inv, o[i][db][4 * g4 + 3] * inv);
;                                 *(u32x2*)(orow + i * 64 + db * 32 + g4 * 8) = w; } }
.LBB0_974:
	v_add_f32_e32 v70, v192, v66
	v_mbcnt_lo_u32_b32 v68, -1, 0
	v_mbcnt_hi_u32_b32 v68, -1, v68
	v_rcp_f32_e32 v0, v0
	v_and_or_b32 v66, v68, 31, s68
	v_ashrrev_i32_e32 v67, 31, v66
	v_lshlrev_b64 v[66:67], 11, v[66:67]
	v_ashrrev_i32_e32 v68, 3, v68
	v_lshl_add_u64 v[66:67], s[10:11], 0, v[66:67]
	s_mov_b32 s81, s17
	v_and_b32_e32 v68, -4, v68
	v_lshl_add_u64 v[66:67], v[66:67], 0, s[80:81]
	v_ashrrev_i32_e32 v69, 31, v68
	v_rcp_f32_e32 v70, v70
	v_lshl_add_u64 v[66:67], v[68:69], 2, v[66:67]
	v_pk_mul_f32 v[34:35], v[0:1], v[34:35] op_sel_hi:[0,1]
	v_pk_mul_f32 v[36:37], v[0:1], v[36:37] op_sel_hi:[0,1]
	v_pk_mul_f32 v[38:39], v[0:1], v[38:39] op_sel_hi:[0,1]
	v_pk_mul_f32 v[40:41], v[0:1], v[40:41] op_sel_hi:[0,1]
	v_cvt_pk_bf16_f32 v34, v34, v35
	v_cvt_pk_bf16_f32 v35, v36, v37
	v_cvt_pk_bf16_f32 v36, v38, v39
	v_cvt_pk_bf16_f32 v37, v40, v41
	v_pk_mul_f32 v[42:43], v[0:1], v[42:43] op_sel_hi:[0,1]
	v_pk_mul_f32 v[44:45], v[0:1], v[44:45] op_sel_hi:[0,1]
	v_pk_mul_f32 v[46:47], v[0:1], v[46:47] op_sel_hi:[0,1]
	v_pk_mul_f32 v[48:49], v[0:1], v[48:49] op_sel_hi:[0,1]
	v_cvt_pk_bf16_f32 v42, v42, v43
	v_cvt_pk_bf16_f32 v43, v44, v45
	v_cvt_pk_bf16_f32 v44, v46, v47
	v_cvt_pk_bf16_f32 v45, v48, v49
	v_permlane32_swap_b32_e32 v34, v36
	v_permlane32_swap_b32_e32 v35, v37
	global_store_dwordx4 v[66:67], v[34:37], off
	v_pk_mul_f32 v[50:51], v[0:1], v[50:51] op_sel_hi:[0,1]
	v_pk_mul_f32 v[52:53], v[0:1], v[52:53] op_sel_hi:[0,1]
	v_pk_mul_f32 v[54:55], v[0:1], v[54:55] op_sel_hi:[0,1]
	v_pk_mul_f32 v[56:57], v[0:1], v[56:57] op_sel_hi:[0,1]
	v_cvt_pk_bf16_f32 v50, v50, v51
	v_cvt_pk_bf16_f32 v51, v52, v53
	v_cvt_pk_bf16_f32 v52, v54, v55
	v_cvt_pk_bf16_f32 v53, v56, v57
	v_permlane32_swap_b32_e32 v42, v44
	v_permlane32_swap_b32_e32 v43, v45
	global_store_dwordx4 v[66:67], v[42:45], off offset:32
	v_pk_mul_f32 v[58:59], v[0:1], v[58:59] op_sel_hi:[0,1]
	v_pk_mul_f32 v[60:61], v[0:1], v[60:61] op_sel_hi:[0,1]
	v_pk_mul_f32 v[62:63], v[0:1], v[62:63] op_sel_hi:[0,1]
	v_pk_mul_f32 v[64:65], v[0:1], v[64:65] op_sel_hi:[0,1]
	v_cvt_pk_bf16_f32 v58, v58, v59
	v_cvt_pk_bf16_f32 v59, v60, v61
	v_cvt_pk_bf16_f32 v60, v62, v63
	v_cvt_pk_bf16_f32 v61, v64, v65
	v_permlane32_swap_b32_e32 v50, v52
	v_permlane32_swap_b32_e32 v51, v53
	global_store_dwordx4 v[66:67], v[50:53], off offset:64
	v_pk_mul_f32 v[18:19], v[70:71], v[18:19] op_sel_hi:[0,1]
	v_pk_mul_f32 v[20:21], v[70:71], v[20:21] op_sel_hi:[0,1]
	v_pk_mul_f32 v[22:23], v[70:71], v[22:23] op_sel_hi:[0,1]
	v_pk_mul_f32 v[24:25], v[70:71], v[24:25] op_sel_hi:[0,1]
	v_cvt_pk_bf16_f32 v18, v18, v19
	v_cvt_pk_bf16_f32 v19, v20, v21
	v_cvt_pk_bf16_f32 v20, v22, v23
	v_cvt_pk_bf16_f32 v21, v24, v25
	v_permlane32_swap_b32_e32 v58, v60
	v_permlane32_swap_b32_e32 v59, v61
	global_store_dwordx4 v[66:67], v[58:61], off offset:96
	v_pk_mul_f32 v[26:27], v[70:71], v[26:27] op_sel_hi:[0,1]
	v_pk_mul_f32 v[28:29], v[70:71], v[28:29] op_sel_hi:[0,1]
	v_pk_mul_f32 v[30:31], v[70:71], v[30:31] op_sel_hi:[0,1]
	v_pk_mul_f32 v[32:33], v[70:71], v[32:33] op_sel_hi:[0,1]
	v_cvt_pk_bf16_f32 v26, v26, v27
	v_cvt_pk_bf16_f32 v27, v28, v29
	v_cvt_pk_bf16_f32 v28, v30, v31
	v_cvt_pk_bf16_f32 v29, v32, v33
	v_permlane32_swap_b32_e32 v18, v20
	v_permlane32_swap_b32_e32 v19, v21
	global_store_dwordx4 v[66:67], v[18:21], off offset:128
	v_pk_mul_f32 v[2:3], v[70:71], v[2:3] op_sel_hi:[0,1]
	v_pk_mul_f32 v[4:5], v[70:71], v[4:5] op_sel_hi:[0,1]
	v_pk_mul_f32 v[6:7], v[70:71], v[6:7] op_sel_hi:[0,1]
	v_pk_mul_f32 v[8:9], v[70:71], v[8:9] op_sel_hi:[0,1]
	v_cvt_pk_bf16_f32 v2, v2, v3
	v_cvt_pk_bf16_f32 v3, v4, v5
	v_cvt_pk_bf16_f32 v4, v6, v7
	v_cvt_pk_bf16_f32 v5, v8, v9
	v_permlane32_swap_b32_e32 v26, v28
	v_permlane32_swap_b32_e32 v27, v29
	global_store_dwordx4 v[66:67], v[26:29], off offset:160
	v_pk_mul_f32 v[10:11], v[70:71], v[10:11] op_sel_hi:[0,1]
	v_pk_mul_f32 v[12:13], v[70:71], v[12:13] op_sel_hi:[0,1]
	v_pk_mul_f32 v[14:15], v[70:71], v[14:15] op_sel_hi:[0,1]
	v_pk_mul_f32 v[16:17], v[70:71], v[16:17] op_sel_hi:[0,1]
	v_cvt_pk_bf16_f32 v10, v10, v11
	v_cvt_pk_bf16_f32 v11, v12, v13
	v_cvt_pk_bf16_f32 v12, v14, v15
	v_cvt_pk_bf16_f32 v13, v16, v17
	v_permlane32_swap_b32_e32 v2, v4
	v_permlane32_swap_b32_e32 v3, v5
	global_store_dwordx4 v[66:67], v[2:5], off offset:192
	s_add_i32 s67, s67, s52
	s_nop 1
	v_permlane32_swap_b32_e32 v10, v12
	v_permlane32_swap_b32_e32 v11, v13
	global_store_dwordx4 v[66:67], v[10:13], off offset:224
	s_cmpk_gt_i32 s67, 0x9ff
	s_cbranch_scc1 .LBB0_1009

; __device__ __forceinline__ int lane_id_asm() { int l; asm volatile("v_mbcnt_lo_u32_b32 %0, -1, 0\n\tv_mbcnt_hi_u32_b32 %0, -1, %0" : "=v"(l)); return l; }
; __device__ __forceinline__ float sum32(float v) { auto rr = __builtin_amdgcn_permlane32_swap(__float_as_uint(v), __float_as_uint(v), false, false); return __uint_as_float(rr[0]) + __uint_as_float(rr[1]); }
; __global__ void __launch_bounds__(NTHREADS, 2) mega_fwd(Params p) {
;     ...
;                     const float ia = __builtin_amdgcn_rcpf(la_[0]), ib = lam * __builtin_amdgcn_rcpf(lb_[0]); float ss = 0.f;
;                     const int l3 = lane_id_asm(), hi2 = l3 >> 5;
;                     bf16_t* orow = Ob + (size_t)(b * T + qb * 256 + wave * 32 + (l3 & 31)) * 1024 + h * 128;
; #pragma unroll
;                     for (int db = 0; db < 4; ++db)
; #pragma unroll
;                         for (int r = 0; r < 16; ++r) { const float v = oa[db][r] * ia - ob[db][r] * ib; oa[db][r] = v; ss += v * v; }
;                     ss = sum32(ss);
;                     const float rinv = rsqrtf(ss * (1.f / 128.f) + EPS) * (1.f - LAM_INIT2);
; #pragma unroll
;                     for (int db = 0; db < 4; ++db)
; #pragma unroll
;                         for (int g4 = 0; g4 < 4; ++g4) { const int d = db * 32 + g4 * 8 + hi2 * 4; const f32x4 gv = *(const f32x4*)(sg + d); u32x2 w;
.LBB0_1323:
	v_add_f32_e32 v2, v228, v3
	v_rcp_f32_e32 v2, v2
	v_rcp_f32_e32 v0, v0
	v_mbcnt_lo_u32_b32 v4, -1, 0
	v_mbcnt_hi_u32_b32 v4, -1, v4
	s_add_i32 s83, s83, s52
	v_mul_f32_e32 v144, s48, v2
	v_and_or_b32 v2, v4, 31, s43
	v_ashrrev_i32_e32 v3, 31, v2
	v_lshlrev_b64 v[2:3], 11, v[2:3]
	v_lshl_add_u64 v[2:3], s[40:41], 0, v[2:3]
	s_mov_b32 s43, s17
	v_pk_mul_f32 v[12:13], v[144:145], v[82:83] op_sel_hi:[0,1]
	v_lshl_add_u64 v[8:9], v[2:3], 0, s[42:43]
	v_ashrrev_i32_e32 v2, 3, v4
	v_pk_fma_f32 v[146:147], v[0:1], v[18:19], v[12:13] op_sel_hi:[0,1,1] neg_lo:[0,0,1] neg_hi:[0,0,1]
	v_pk_mul_f32 v[12:13], v[144:145], v[80:81] op_sel_hi:[0,1]
	v_and_b32_e32 v10, -4, v2
	v_pk_fma_f32 v[148:149], v[0:1], v[16:17], v[12:13] op_sel_hi:[0,1,1] neg_lo:[0,0,1] neg_hi:[0,0,1]
	v_ashrrev_i32_e32 v11, 31, v10
	v_mul_f32_e32 v12, v149, v149
	v_lshl_add_u64 v[6:7], v[10:11], 2, s[36:37]
	global_load_dwordx4 v[160:163], v[6:7], off
	global_load_dwordx4 v[164:167], v[6:7], off offset:32
	global_load_dwordx4 v[168:171], v[6:7], off offset:64
	global_load_dwordx4 v[172:175], v[6:7], off offset:96
	global_load_dwordx4 v[176:179], v[6:7], off offset:128
	global_load_dwordx4 v[180:183], v[6:7], off offset:160
	global_load_dwordx4 v[184:187], v[6:7], off offset:192
	global_load_dwordx4 v[188:191], v[6:7], off offset:224
	global_load_dwordx4 v[192:195], v[6:7], off offset:256
	global_load_dwordx4 v[196:199], v[6:7], off offset:288
	global_load_dwordx4 v[200:203], v[6:7], off offset:320
	global_load_dwordx4 v[204:207], v[6:7], off offset:352
	global_load_dwordx4 v[216:219], v[6:7], off offset:384
	global_load_dwordx4 v[220:223], v[6:7], off offset:416
	global_load_dwordx4 v[238:241], v[6:7], off offset:448
	global_load_dwordx4 v[242:245], v[6:7], off offset:480
	v_pk_fma_f32 v[12:13], v[148:149], v[148:149], v[12:13] op_sel_hi:[1,1,0]
	v_lshl_add_u64 v[8:9], v[10:11], 2, v[8:9]
	v_pk_mul_f32 v[10:11], v[144:145], v[86:87] op_sel_hi:[0,1]
	v_pk_fma_f32 v[12:13], v[146:147], v[146:147], v[12:13]
	v_mul_f32_e32 v14, v147, v147
	v_pk_fma_f32 v[150:151], v[0:1], v[22:23], v[10:11] op_sel_hi:[0,1,1] neg_lo:[0,0,1] neg_hi:[0,0,1]
	v_pk_mul_f32 v[10:11], v[144:145], v[84:85] op_sel_hi:[0,1]
	v_pk_add_f32 v[12:13], v[12:13], v[14:15] op_sel_hi:[1,0]
	v_pk_fma_f32 v[152:153], v[0:1], v[20:21], v[10:11] op_sel_hi:[0,1,1] neg_lo:[0,0,1] neg_hi:[0,0,1]
	v_pk_fma_f32 v[10:11], v[152:153], v[152:153], v[12:13]
	v_mul_f32_e32 v12, v153, v153
	v_pk_add_f32 v[10:11], v[10:11], v[12:13] op_sel_hi:[1,0]
	v_mul_f32_e32 v12, v151, v151
	v_pk_fma_f32 v[10:11], v[150:151], v[150:151], v[10:11]
	v_pk_add_f32 v[10:11], v[10:11], v[12:13] op_sel_hi:[1,0]
	v_pk_mul_f32 v[12:13], v[144:145], v[90:91] op_sel_hi:[0,1]
	v_pk_fma_f32 v[90:91], v[0:1], v[26:27], v[12:13] op_sel_hi:[0,1,1] neg_lo:[0,0,1] neg_hi:[0,0,1]
	v_pk_mul_f32 v[12:13], v[144:145], v[88:89] op_sel_hi:[0,1]
	v_pk_fma_f32 v[154:155], v[0:1], v[24:25], v[12:13] op_sel_hi:[0,1,1] neg_lo:[0,0,1] neg_hi:[0,0,1]
	v_pk_fma_f32 v[10:11], v[154:155], v[154:155], v[10:11]
	v_mul_f32_e32 v12, v155, v155
	v_pk_add_f32 v[10:11], v[10:11], v[12:13] op_sel_hi:[1,0]
	v_mul_f32_e32 v12, v91, v91
	v_pk_fma_f32 v[10:11], v[90:91], v[90:91], v[10:11]
	v_pk_mul_f32 v[16:17], v[144:145], v[104:105] op_sel_hi:[0,1]
	v_pk_add_f32 v[10:11], v[10:11], v[12:13] op_sel_hi:[1,0]
	v_pk_mul_f32 v[12:13], v[144:145], v[94:95] op_sel_hi:[0,1]
	v_pk_fma_f32 v[86:87], v[0:1], v[30:31], v[12:13] op_sel_hi:[0,1,1] neg_lo:[0,0,1] neg_hi:[0,0,1]
	v_pk_mul_f32 v[12:13], v[144:145], v[92:93] op_sel_hi:[0,1]
	v_pk_fma_f32 v[92:93], v[0:1], v[28:29], v[12:13] op_sel_hi:[0,1,1] neg_lo:[0,0,1] neg_hi:[0,0,1]
	v_pk_fma_f32 v[10:11], v[92:93], v[92:93], v[10:11]
	v_mul_f32_e32 v12, v93, v93
	v_pk_add_f32 v[10:11], v[10:11], v[12:13] op_sel_hi:[1,0]
	v_mul_f32_e32 v12, v87, v87
	v_pk_fma_f32 v[10:11], v[86:87], v[86:87], v[10:11]
	v_pk_fma_f32 v[18:19], v[0:1], v[40:41], v[16:17] op_sel_hi:[0,1,1] neg_lo:[0,0,1] neg_hi:[0,0,1]
	v_pk_add_f32 v[10:11], v[10:11], v[12:13] op_sel_hi:[1,0]
	v_pk_mul_f32 v[12:13], v[144:145], v[130:131] op_sel_hi:[0,1]
	v_pk_fma_f32 v[82:83], v[0:1], v[66:67], v[12:13] op_sel_hi:[0,1,1] neg_lo:[0,0,1] neg_hi:[0,0,1]
	v_pk_mul_f32 v[12:13], v[144:145], v[128:129] op_sel_hi:[0,1]
	v_pk_fma_f32 v[88:89], v[0:1], v[64:65], v[12:13] op_sel_hi:[0,1,1] neg_lo:[0,0,1] neg_hi:[0,0,1]
	v_pk_fma_f32 v[10:11], v[88:89], v[88:89], v[10:11]
	v_mul_f32_e32 v12, v89, v89
	v_pk_add_f32 v[10:11], v[10:11], v[12:13] op_sel_hi:[1,0]
	v_mul_f32_e32 v12, v83, v83
	v_pk_fma_f32 v[10:11], v[82:83], v[82:83], v[10:11]
	v_mul_f32_e32 v16, v19, v19
	v_pk_add_f32 v[10:11], v[10:11], v[12:13] op_sel_hi:[1,0]
	v_pk_mul_f32 v[12:13], v[144:145], v[134:135] op_sel_hi:[0,1]
	v_pk_fma_f32 v[80:81], v[0:1], v[70:71], v[12:13] op_sel_hi:[0,1,1] neg_lo:[0,0,1] neg_hi:[0,0,1]
	v_pk_mul_f32 v[12:13], v[144:145], v[132:133] op_sel_hi:[0,1]
	v_pk_fma_f32 v[84:85], v[0:1], v[68:69], v[12:13] op_sel_hi:[0,1,1] neg_lo:[0,0,1] neg_hi:[0,0,1]
	v_pk_fma_f32 v[10:11], v[84:85], v[84:85], v[10:11]
	v_mul_f32_e32 v12, v85, v85
	v_pk_add_f32 v[10:11], v[10:11], v[12:13] op_sel_hi:[1,0]
	v_mul_f32_e32 v12, v81, v81
	v_pk_fma_f32 v[10:11], v[80:81], v[80:81], v[10:11]
	s_cmpk_gt_i32 s83, 0x9ff
	v_pk_add_f32 v[10:11], v[10:11], v[12:13] op_sel_hi:[1,0]
	v_pk_mul_f32 v[12:13], v[144:145], v[138:139] op_sel_hi:[0,1]
	v_pk_fma_f32 v[70:71], v[0:1], v[74:75], v[12:13] op_sel_hi:[0,1,1] neg_lo:[0,0,1] neg_hi:[0,0,1]
	v_pk_mul_f32 v[12:13], v[144:145], v[136:137] op_sel_hi:[0,1]
	v_pk_fma_f32 v[74:75], v[0:1], v[72:73], v[12:13] op_sel_hi:[0,1,1] neg_lo:[0,0,1] neg_hi:[0,0,1]
; __device__ __forceinline__ float sum32(float v) { auto rr = __builtin_amdgcn_permlane32_swap(__float_as_uint(v), __float_as_uint(v), false, false); return __uint_as_float(rr[0]) + __uint_as_float(rr[1]); }
; __global__ void __launch_bounds__(NTHREADS, 2) mega_fwd(Params p) {
;     ...
;                         for (int r = 0; r < 16; ++r) { const float v = oa[db][r] * ia - ob[db][r] * ib; oa[db][r] = v; ss += v * v; }
;                     ss = sum32(ss);
;                     const float rinv = rsqrtf(ss * (1.f / 128.f) + EPS) * (1.f - LAM_INIT2);
	v_pk_fma_f32 v[10:11], v[74:75], v[74:75], v[10:11]
	v_mul_f32_e32 v12, v75, v75
	v_pk_add_f32 v[10:11], v[10:11], v[12:13] op_sel_hi:[1,0]
	v_mul_f32_e32 v12, v71, v71
	v_pk_fma_f32 v[10:11], v[70:71], v[70:71], v[10:11]
	s_nop 0
	v_pk_add_f32 v[10:11], v[10:11], v[12:13] op_sel_hi:[1,0]
	v_pk_mul_f32 v[12:13], v[144:145], v[142:143] op_sel_hi:[0,1]
	v_pk_fma_f32 v[66:67], v[0:1], v[78:79], v[12:13] op_sel_hi:[0,1,1] neg_lo:[0,0,1] neg_hi:[0,0,1]
	v_pk_mul_f32 v[12:13], v[144:145], v[140:141] op_sel_hi:[0,1]
	v_pk_fma_f32 v[72:73], v[0:1], v[76:77], v[12:13] op_sel_hi:[0,1,1] neg_lo:[0,0,1] neg_hi:[0,0,1]
	v_pk_fma_f32 v[10:11], v[72:73], v[72:73], v[10:11]
	v_mul_f32_e32 v12, v73, v73
	v_pk_add_f32 v[10:11], v[10:11], v[12:13] op_sel_hi:[1,0]
	v_mul_f32_e32 v12, v67, v67
	v_pk_fma_f32 v[10:11], v[66:67], v[66:67], v[10:11]
	s_nop 0
	v_pk_add_f32 v[10:11], v[10:11], v[12:13] op_sel_hi:[1,0]
	v_pk_mul_f32 v[12:13], v[144:145], v[114:115] op_sel_hi:[0,1]
	v_pk_fma_f32 v[64:65], v[0:1], v[50:51], v[12:13] op_sel_hi:[0,1,1] neg_lo:[0,0,1] neg_hi:[0,0,1]
	v_pk_mul_f32 v[12:13], v[144:145], v[112:113] op_sel_hi:[0,1]
	v_pk_fma_f32 v[68:69], v[0:1], v[48:49], v[12:13] op_sel_hi:[0,1,1] neg_lo:[0,0,1] neg_hi:[0,0,1]
	v_pk_fma_f32 v[10:11], v[68:69], v[68:69], v[10:11]
	v_mul_f32_e32 v12, v69, v69
	v_pk_add_f32 v[10:11], v[10:11], v[12:13] op_sel_hi:[1,0]
	v_mul_f32_e32 v12, v65, v65
	v_pk_fma_f32 v[10:11], v[64:65], v[64:65], v[10:11]
	s_nop 0
	v_pk_add_f32 v[10:11], v[10:11], v[12:13] op_sel_hi:[1,0]
	v_pk_mul_f32 v[12:13], v[144:145], v[118:119] op_sel_hi:[0,1]
	v_pk_fma_f32 v[30:31], v[0:1], v[54:55], v[12:13] op_sel_hi:[0,1,1] neg_lo:[0,0,1] neg_hi:[0,0,1]
	v_pk_mul_f32 v[12:13], v[144:145], v[116:117] op_sel_hi:[0,1]
	v_pk_fma_f32 v[52:53], v[0:1], v[52:53], v[12:13] op_sel_hi:[0,1,1] neg_lo:[0,0,1] neg_hi:[0,0,1]
	v_pk_fma_f32 v[10:11], v[52:53], v[52:53], v[10:11]
	v_mul_f32_e32 v12, v53, v53
	v_pk_add_f32 v[10:11], v[10:11], v[12:13] op_sel_hi:[1,0]
	v_mul_f32_e32 v12, v31, v31
	v_pk_fma_f32 v[10:11], v[30:31], v[30:31], v[10:11]
	s_nop 0
	v_pk_add_f32 v[10:11], v[10:11], v[12:13] op_sel_hi:[1,0]
	v_pk_mul_f32 v[12:13], v[144:145], v[122:123] op_sel_hi:[0,1]
	v_pk_fma_f32 v[28:29], v[0:1], v[58:59], v[12:13] op_sel_hi:[0,1,1] neg_lo:[0,0,1] neg_hi:[0,0,1]
	v_pk_mul_f32 v[12:13], v[144:145], v[120:121] op_sel_hi:[0,1]
	v_pk_fma_f32 v[50:51], v[0:1], v[56:57], v[12:13] op_sel_hi:[0,1,1] neg_lo:[0,0,1] neg_hi:[0,0,1]
	v_pk_fma_f32 v[10:11], v[50:51], v[50:51], v[10:11]
	v_mul_f32_e32 v12, v51, v51
	v_pk_add_f32 v[10:11], v[10:11], v[12:13] op_sel_hi:[1,0]
	v_mul_f32_e32 v12, v29, v29
	v_pk_fma_f32 v[10:11], v[28:29], v[28:29], v[10:11]
	s_nop 0
	v_pk_add_f32 v[10:11], v[10:11], v[12:13] op_sel_hi:[1,0]
	v_pk_mul_f32 v[12:13], v[144:145], v[126:127] op_sel_hi:[0,1]
	v_pk_fma_f32 v[24:25], v[0:1], v[62:63], v[12:13] op_sel_hi:[0,1,1] neg_lo:[0,0,1] neg_hi:[0,0,1]
	v_pk_mul_f32 v[12:13], v[144:145], v[124:125] op_sel_hi:[0,1]
	v_pk_fma_f32 v[48:49], v[0:1], v[60:61], v[12:13] op_sel_hi:[0,1,1] neg_lo:[0,0,1] neg_hi:[0,0,1]
	v_pk_fma_f32 v[10:11], v[48:49], v[48:49], v[10:11]
	v_mul_f32_e32 v12, v49, v49
	v_pk_add_f32 v[10:11], v[10:11], v[12:13] op_sel_hi:[1,0]
	v_mul_f32_e32 v12, v25, v25
	v_pk_fma_f32 v[10:11], v[24:25], v[24:25], v[10:11]
	s_nop 0
	v_pk_add_f32 v[10:11], v[10:11], v[12:13] op_sel_hi:[1,0]
	v_pk_mul_f32 v[12:13], v[144:145], v[98:99] op_sel_hi:[0,1]
	v_pk_fma_f32 v[20:21], v[0:1], v[34:35], v[12:13] op_sel_hi:[0,1,1] neg_lo:[0,0,1] neg_hi:[0,0,1]
	v_pk_mul_f32 v[12:13], v[144:145], v[96:97] op_sel_hi:[0,1]
	v_pk_fma_f32 v[26:27], v[0:1], v[32:33], v[12:13] op_sel_hi:[0,1,1] neg_lo:[0,0,1] neg_hi:[0,0,1]
	v_pk_fma_f32 v[10:11], v[26:27], v[26:27], v[10:11]
	v_mul_f32_e32 v12, v27, v27
	v_pk_add_f32 v[10:11], v[10:11], v[12:13] op_sel_hi:[1,0]
	v_mul_f32_e32 v12, v21, v21
	v_pk_fma_f32 v[10:11], v[20:21], v[20:21], v[10:11]
	s_nop 0
	v_pk_add_f32 v[10:11], v[10:11], v[12:13] op_sel_hi:[1,0]
	v_pk_mul_f32 v[12:13], v[144:145], v[102:103] op_sel_hi:[0,1]
	v_pk_fma_f32 v[14:15], v[0:1], v[38:39], v[12:13] op_sel_hi:[0,1,1] neg_lo:[0,0,1] neg_hi:[0,0,1]
	v_pk_mul_f32 v[12:13], v[144:145], v[100:101] op_sel_hi:[0,1]
	v_pk_fma_f32 v[22:23], v[0:1], v[36:37], v[12:13] op_sel_hi:[0,1,1] neg_lo:[0,0,1] neg_hi:[0,0,1]
	v_pk_fma_f32 v[10:11], v[22:23], v[22:23], v[10:11]
	v_mul_f32_e32 v12, v23, v23
	v_pk_add_f32 v[10:11], v[10:11], v[12:13] op_sel_hi:[1,0]
	v_mul_f32_e32 v12, v15, v15
	v_pk_fma_f32 v[10:11], v[14:15], v[14:15], v[10:11]
	s_nop 0
	v_pk_add_f32 v[12:13], v[10:11], v[12:13] op_sel_hi:[1,0]
	v_pk_mul_f32 v[10:11], v[144:145], v[106:107] op_sel_hi:[0,1]
	v_pk_fma_f32 v[12:13], v[18:19], v[18:19], v[12:13]
	v_pk_fma_f32 v[10:11], v[0:1], v[42:43], v[10:11] op_sel_hi:[0,1,1] neg_lo:[0,0,1] neg_hi:[0,0,1]
	v_pk_add_f32 v[12:13], v[12:13], v[16:17] op_sel_hi:[1,0]
	v_mul_f32_e32 v16, v11, v11
	v_pk_fma_f32 v[12:13], v[10:11], v[10:11], v[12:13]
	s_nop 0
	v_pk_add_f32 v[32:33], v[12:13], v[16:17] op_sel_hi:[1,0]
	v_pk_mul_f32 v[16:17], v[144:145], v[108:109] op_sel_hi:[0,1]
	v_pk_mul_f32 v[12:13], v[144:145], v[110:111] op_sel_hi:[0,1]
	v_pk_fma_f32 v[16:17], v[0:1], v[44:45], v[16:17] op_sel_hi:[0,1,1] neg_lo:[0,0,1] neg_hi:[0,0,1]
	v_pk_fma_f32 v[12:13], v[0:1], v[46:47], v[12:13] op_sel_hi:[0,1,1] neg_lo:[0,0,1] neg_hi:[0,0,1]
	v_pk_fma_f32 v[32:33], v[16:17], v[16:17], v[32:33]
	v_mul_f32_e32 v0, v17, v17
	v_pk_add_f32 v[32:33], v[32:33], v[0:1] op_sel_hi:[1,0]
	v_mul_f32_e32 v0, v13, v13
	v_pk_fma_f32 v[32:33], v[12:13], v[12:13], v[32:33]
	s_nop 0
	v_pk_add_f32 v[32:33], v[32:33], v[0:1] op_sel_hi:[1,0]
	s_nop 0
	v_mov_b32_e32 v0, v32
	s_nop 1
	v_permlane32_swap_b32_e32 v32, v0
	v_add_f32_e32 v0, v32, v0
	v_fmamk_f32 v0, v0, 0x3c000000, v254
	v_cmp_gt_f32_e32 vcc, s56, v0
	v_mul_f32_e32 v32, 0x4b800000, v0
	s_nop 0
	v_cndmask_b32_e32 v0, v0, v32, vcc
	v_rsq_f32_e32 v0, v0
	s_nop 0
	v_mul_f32_e32 v32, 0x45800000, v0
	v_cndmask_b32_e32 v0, v0, v32, vcc
	v_mul_f32_e32 v0, 0x3f077f5a, v0
	v_pk_mul_f32 v[32:33], v[0:1], v[148:149] op_sel_hi:[0,1]
	s_waitcnt vmcnt(15)
; __device__ __forceinline__ unsigned cvtpk(float lo, float hi) { f32x2 v = {lo, hi}; bf16x2_t b = __builtin_convertvector(v, bf16x2_t); return __builtin_bit_cast(unsigned, b); }
; __global__ void __launch_bounds__(NTHREADS, 2) mega_fwd(Params p) {
;     ...
;                     for (int db = 0; db < 4; ++db)
; #pragma unroll
;                         for (int g4 = 0; g4 < 4; ++g4) { const int d = db * 32 + g4 * 8 + hi2 * 4; const f32x4 gv = *(const f32x4*)(sg + d); u32x2 w;
;                             w.x = cvtpk(oa[db][4 * g4] * rinv * gv.x, oa[db][4 * g4 + 1] * rinv * gv.y); w.y = cvtpk(oa[db][4 * g4 + 2] * rinv * gv.z, oa[db][4 * g4 + 3] * rinv * gv.w);
;                             *(u32x2*)(orow + d) = w; }
	v_pk_mul_f32 v[2:3], v[160:161], v[32:33]
	v_pk_mul_f32 v[32:33], v[0:1], v[146:147] op_sel_hi:[0,1]
	v_pk_mul_f32 v[4:5], v[162:163], v[32:33]
	v_cvt_pk_bf16_f32 v2, v2, v3
	v_cvt_pk_bf16_f32 v3, v4, v5
	v_pk_mul_f32 v[32:33], v[0:1], v[152:153] op_sel_hi:[0,1]
	v_pk_mul_f32 v[30:31], v[0:1], v[30:31] op_sel_hi:[0,1]
	v_pk_mul_f32 v[28:29], v[0:1], v[28:29] op_sel_hi:[0,1]
	v_pk_mul_f32 v[24:25], v[0:1], v[24:25] op_sel_hi:[0,1]
	v_pk_mul_f32 v[20:21], v[0:1], v[20:21] op_sel_hi:[0,1]
	v_pk_mul_f32 v[14:15], v[0:1], v[14:15] op_sel_hi:[0,1]
	v_pk_mul_f32 v[10:11], v[0:1], v[10:11] op_sel_hi:[0,1]
	s_waitcnt vmcnt(14)
	v_pk_mul_f32 v[160:161], v[164:165], v[32:33]
	v_pk_mul_f32 v[32:33], v[0:1], v[150:151] op_sel_hi:[0,1]
	v_pk_mul_f32 v[162:163], v[166:167], v[32:33]
	v_cvt_pk_bf16_f32 v4, v160, v161
	v_cvt_pk_bf16_f32 v5, v162, v163
	s_nop 1
	v_permlane32_swap_b32_e32 v2, v4
	v_permlane32_swap_b32_e32 v3, v5
	global_store_dwordx4 v[8:9], v[2:5], off
	v_pk_mul_f32 v[32:33], v[0:1], v[154:155] op_sel_hi:[0,1]
	s_waitcnt vmcnt(14)
	v_pk_mul_f32 v[2:3], v[168:169], v[32:33]
	v_pk_mul_f32 v[32:33], v[0:1], v[90:91] op_sel_hi:[0,1]
	v_pk_mul_f32 v[4:5], v[170:171], v[32:33]
	v_cvt_pk_bf16_f32 v2, v2, v3
	v_cvt_pk_bf16_f32 v3, v4, v5
	v_pk_mul_f32 v[32:33], v[0:1], v[92:93] op_sel_hi:[0,1]
	s_waitcnt vmcnt(13)
	v_pk_mul_f32 v[168:169], v[172:173], v[32:33]
	v_pk_mul_f32 v[32:33], v[0:1], v[86:87] op_sel_hi:[0,1]
	v_pk_mul_f32 v[170:171], v[174:175], v[32:33]
	v_cvt_pk_bf16_f32 v4, v168, v169
	v_cvt_pk_bf16_f32 v5, v170, v171
	s_nop 1
	v_permlane32_swap_b32_e32 v2, v4
	v_permlane32_swap_b32_e32 v3, v5
	global_store_dwordx4 v[8:9], v[2:5], off offset:32
	v_pk_mul_f32 v[32:33], v[0:1], v[88:89] op_sel_hi:[0,1]
	s_waitcnt vmcnt(13)
	v_pk_mul_f32 v[2:3], v[176:177], v[32:33]
	v_pk_mul_f32 v[32:33], v[0:1], v[82:83] op_sel_hi:[0,1]
	v_pk_mul_f32 v[4:5], v[178:179], v[32:33]
	v_cvt_pk_bf16_f32 v2, v2, v3
	v_cvt_pk_bf16_f32 v3, v4, v5
	v_pk_mul_f32 v[32:33], v[0:1], v[84:85] op_sel_hi:[0,1]
	s_waitcnt vmcnt(12)
	v_pk_mul_f32 v[176:177], v[180:181], v[32:33]
	v_pk_mul_f32 v[32:33], v[0:1], v[80:81] op_sel_hi:[0,1]
	v_pk_mul_f32 v[178:179], v[182:183], v[32:33]
	v_cvt_pk_bf16_f32 v4, v176, v177
	v_cvt_pk_bf16_f32 v5, v178, v179
	s_nop 1
	v_permlane32_swap_b32_e32 v2, v4
	v_permlane32_swap_b32_e32 v3, v5
	global_store_dwordx4 v[8:9], v[2:5], off offset:64
	v_pk_mul_f32 v[32:33], v[0:1], v[74:75] op_sel_hi:[0,1]
	s_waitcnt vmcnt(12)
	v_pk_mul_f32 v[2:3], v[184:185], v[32:33]
	v_pk_mul_f32 v[32:33], v[0:1], v[70:71] op_sel_hi:[0,1]
	v_pk_mul_f32 v[4:5], v[186:187], v[32:33]
	v_cvt_pk_bf16_f32 v2, v2, v3
	v_cvt_pk_bf16_f32 v3, v4, v5
	v_pk_mul_f32 v[32:33], v[0:1], v[72:73] op_sel_hi:[0,1]
	s_waitcnt vmcnt(11)
	v_pk_mul_f32 v[184:185], v[188:189], v[32:33]
	v_pk_mul_f32 v[32:33], v[0:1], v[66:67] op_sel_hi:[0,1]
	v_pk_mul_f32 v[186:187], v[190:191], v[32:33]
	v_cvt_pk_bf16_f32 v4, v184, v185
	v_cvt_pk_bf16_f32 v5, v186, v187
	s_nop 1
	v_permlane32_swap_b32_e32 v2, v4
	v_permlane32_swap_b32_e32 v3, v5
	global_store_dwordx4 v[8:9], v[2:5], off offset:96
	v_pk_mul_f32 v[32:33], v[0:1], v[68:69] op_sel_hi:[0,1]
	s_waitcnt vmcnt(11)
	v_pk_mul_f32 v[2:3], v[192:193], v[32:33]
	v_pk_mul_f32 v[32:33], v[0:1], v[64:65] op_sel_hi:[0,1]
	v_pk_mul_f32 v[4:5], v[194:195], v[32:33]
	v_cvt_pk_bf16_f32 v2, v2, v3
	v_cvt_pk_bf16_f32 v3, v4, v5
	v_pk_mul_f32 v[32:33], v[0:1], v[52:53] op_sel_hi:[0,1]
	s_waitcnt vmcnt(10)
	v_pk_mul_f32 v[192:193], v[196:197], v[32:33]
	v_pk_mul_f32 v[194:195], v[198:199], v[30:31]
	v_cvt_pk_bf16_f32 v4, v192, v193
	v_cvt_pk_bf16_f32 v5, v194, v195
	s_nop 1
	v_permlane32_swap_b32_e32 v2, v4
	v_permlane32_swap_b32_e32 v3, v5
	global_store_dwordx4 v[8:9], v[2:5], off offset:128
	v_pk_mul_f32 v[30:31], v[0:1], v[50:51] op_sel_hi:[0,1]
	s_waitcnt vmcnt(10)
	v_pk_mul_f32 v[2:3], v[200:201], v[30:31]
	v_pk_mul_f32 v[4:5], v[202:203], v[28:29]
	v_cvt_pk_bf16_f32 v2, v2, v3
	v_cvt_pk_bf16_f32 v3, v4, v5
	v_pk_mul_f32 v[28:29], v[0:1], v[48:49] op_sel_hi:[0,1]
	s_waitcnt vmcnt(9)
	v_pk_mul_f32 v[200:201], v[204:205], v[28:29]
	v_pk_mul_f32 v[202:203], v[206:207], v[24:25]
	v_cvt_pk_bf16_f32 v4, v200, v201
	v_cvt_pk_bf16_f32 v5, v202, v203
	s_nop 1
	v_permlane32_swap_b32_e32 v2, v4
	v_permlane32_swap_b32_e32 v3, v5
	global_store_dwordx4 v[8:9], v[2:5], off offset:160
	v_pk_mul_f32 v[24:25], v[0:1], v[26:27] op_sel_hi:[0,1]
	s_waitcnt vmcnt(9)
	v_pk_mul_f32 v[2:3], v[216:217], v[24:25]
	v_pk_mul_f32 v[4:5], v[218:219], v[20:21]
	v_cvt_pk_bf16_f32 v2, v2, v3
	v_cvt_pk_bf16_f32 v3, v4, v5
	v_pk_mul_f32 v[20:21], v[0:1], v[22:23] op_sel_hi:[0,1]
	s_waitcnt vmcnt(8)
	v_pk_mul_f32 v[216:217], v[220:221], v[20:21]
	v_pk_mul_f32 v[218:219], v[222:223], v[14:15]
	v_cvt_pk_bf16_f32 v4, v216, v217
	v_cvt_pk_bf16_f32 v5, v218, v219
	s_nop 1
	v_permlane32_swap_b32_e32 v2, v4
	v_permlane32_swap_b32_e32 v3, v5
	global_store_dwordx4 v[8:9], v[2:5], off offset:192
	v_pk_mul_f32 v[14:15], v[0:1], v[18:19] op_sel_hi:[0,1]
	s_waitcnt vmcnt(8)
	v_pk_mul_f32 v[2:3], v[238:239], v[14:15]
	v_pk_mul_f32 v[4:5], v[240:241], v[10:11]
	v_cvt_pk_bf16_f32 v2, v2, v3
	v_cvt_pk_bf16_f32 v3, v4, v5
	v_pk_mul_f32 v[6:7], v[0:1], v[16:17] op_sel_hi:[0,1]
	s_waitcnt vmcnt(7)
	v_pk_mul_f32 v[238:239], v[242:243], v[6:7]
	v_pk_mul_f32 v[6:7], v[0:1], v[12:13] op_sel_hi:[0,1]
	v_pk_mul_f32 v[240:241], v[244:245], v[6:7]
	v_cvt_pk_bf16_f32 v4, v238, v239
	v_cvt_pk_bf16_f32 v5, v240, v241
	s_nop 1
	v_permlane32_swap_b32_e32 v2, v4
	v_permlane32_swap_b32_e32 v3, v5
	global_store_dwordx4 v[8:9], v[2:5], off offset:224
	s_cbranch_scc1 .LBB0_1413
